# strategy 4: static s_setprio 1 for waves 4-7 during the P2 attention run (reset to 0 afterwards)
# speedup vs baseline: 1.0024x; 1.0024x over previous
.Lstag_attn:
	v_readfirstlane_b32 s98, v222
	s_cmp_ge_u32 s98, 0x100
	s_cbranch_scc0 .Lprio_attn
	s_setprio 1

.LBB0_419:
	s_setprio 0
	s_cmpk_lt_i32 s88, 0x400
	s_cselect_b64 s[4:5], -1, 0
	s_cmpk_gt_i32 s88, 0x3ff
	s_cbranch_scc1 .LBB0_422
	v_lshlrev_b32_e32 v0, 4, v209
	s_waitcnt lgkmcnt(3)
	v_and_b32_e32 v2, 0x70, v0
	s_waitcnt lgkmcnt(2)
	v_mov_b32_e32 v3, 0
	v_lshl_add_u64 v[0:1], s[68:69], 0, v[2:3]
	v_add_u32_e32 v18, 0, v2
	v_sub_u32_e32 v2, 0x7f, v112
	s_waitcnt vmcnt(9)
	v_cvt_f32_i32_e32 v12, v2
	v_add_u32_e32 v2, 0x200, v209
	v_ashrrev_i32_e32 v2, 3, v2
	v_sub_u32_e32 v4, 0x7f, v2
	v_cvt_f32_i32_e32 v13, v4
	v_lshrrev_b32_e32 v4, 5, v209
	s_waitcnt lgkmcnt(1)
	v_bfe_u32 v6, v209, 2, 2
	v_and_b32_e32 v4, 2, v4
	v_ashrrev_i32_e32 v5, 7, v209
	s_waitcnt lgkmcnt(0)
	v_and_b32_e32 v7, 24, v119
	v_lshlrev_b32_e32 v9, 8, v193
	v_lshl_or_b32 v6, v193, 3, v6
	v_add_u32_e32 v8, 0, v7
	v_lshlrev_b32_e32 v10, 5, v4
	s_waitcnt vmcnt(8)
	v_mul_u32_u24_e32 v23, 0x90, v6
	v_lshl_or_b32 v6, v5, 10, v9
	v_lshl_or_b32 v4, v4, 4, v189
	v_add3_u32 v22, 0, v10, v7
	s_waitcnt vmcnt(7)
	v_add3_u32 v24, v8, v10, 32
	v_or_b32_e32 v10, v4, v6
	v_or_b32_e32 v14, 16, v10
	v_lshl_add_u32 v21, v5, 5, v8
	v_ashrrev_i32_e32 v15, 31, v14
	v_mov_b64_e32 v[8:9], 0xb400000
	s_movk_i32 s0, 0x90
	s_lshl_b32 s12, s88, 7
	s_lshl_b32 s13, s26, 7
	v_lshl_add_u64 v[4:5], v[14:15], 2, v[8:9]
	s_lshl_b64 s[2:3], s[88:89], 14
	v_ashrrev_i32_e32 v15, 31, v6
	v_ashrrev_i32_e32 v11, 31, v10
	v_mul_lo_u32 v19, v112, s0
	v_mul_lo_u32 v20, v2, s0
	s_add_u32 s2, s24, s2
	v_mov_b64_e32 v[16:17], 0xb400200
	v_lshl_add_u64 v[8:9], v[10:11], 2, v[8:9]
	v_mov_b32_e32 v11, v15
	s_mov_b32 s1, 0
	v_ashrrev_i32_e32 v113, 31, v112
	v_ashrrev_i32_e32 v3, 31, v2
	s_addc_u32 s3, s25, s3
	s_lshl_b64 s[8:9], s[28:29], 14
	v_lshl_add_u64 v[6:7], v[14:15], 2, v[16:17]
	v_lshl_add_u64 v[10:11], v[10:11], 2, v[16:17]
	s_mov_b32 s14, 0x800000
	s_mov_b32 s15, 0x3f317217
	s_mov_b32 s16, 0x7f800000
	v_mov_b32_e32 v14, 0x41b17218
	s_movk_i32 s17, 0x1c00
	v_add_u32_e32 v15, v18, v19
	v_add_u32_e32 v16, v18, v20
	v_add_u32_e32 v17, v21, v23
	v_add_u32_e32 v18, v22, v23
	v_add_u32_e32 v19, v24, v23
	s_mov_b32 s18, s88
